# final-norm pipelined + FFN-up epilogue: the two serialized parameter-load round trips merged into one (cmax via 4 dword loads into free VGPRs, first vmcnt(0) removed)
# speedup vs baseline: 1.0065x; 1.0013x over previous
.LBB0_1217:
	v_lshl_add_u32 v198, s29, 8, v205
	v_or_b32_e32 v192, 16, v198
	v_ashrrev_i32_e32 v199, 31, v198
	v_ashrrev_i32_e32 v193, 31, v192
	v_or_b32_e32 v190, 32, v198
	v_lshl_or_b32 v194, s28, 7, v209
	v_lshl_add_u64 v[130:131], v[198:199], 2, s[10:11]
	v_lshl_add_u64 v[132:133], v[192:193], 2, s[10:11]
	v_ashrrev_i32_e32 v191, 31, v190
	v_or_b32_e32 v188, 48, v198
	v_ashrrev_i32_e32 v195, 31, v194
	global_load_dword v220, v[130:131], off
	global_load_dword v219, v[132:133], off
	global_load_dword v216, v[130:131], off offset:512
	global_load_dword v215, v[130:131], off offset:576
	global_load_dword v214, v[130:131], off offset:640
	global_load_dword v211, v[130:131], off offset:704
	v_lshl_add_u64 v[132:133], v[190:191], 2, s[10:11]
	v_ashrrev_i32_e32 v189, 31, v188
	v_lshlrev_b32_e32 v254, 2, v194
	global_load_dword v218, v[132:133], off
	v_lshl_add_u64 v[132:133], v[188:189], 2, s[10:11]
	global_load_dword v217, v[132:133], off
	global_load_dword v252, v254, s[14:15] offset:16
	s_mov_b32 s28, 0x3c010204
	global_load_dword v250, v254, s[14:15]
	v_add_u32_e32 v186, 0x80, v198
	global_load_dword v253, v254, s[20:21] offset:16
	v_ashrrev_i32_e32 v187, 31, v186
	global_load_dword v251, v254, s[20:21]
	v_lshlrev_b64 v[138:139], 5, v[188:189]
	v_lshl_add_u64 v[138:139], s[8:9], 0, v[138:139]
	v_lshlrev_b64 v[154:155], 5, v[186:187]
	v_lshl_add_u64 v[154:155], s[8:9], 0, v[154:155]
	v_add_u32_e32 v184, 0x90, v198
	v_ashrrev_i32_e32 v185, 31, v184
	v_add_u32_e32 v182, 0xa0, v198
	v_ashrrev_i32_e32 v183, 31, v182
	v_add_u32_e32 v180, 0xb0, v198
	v_ashrrev_i32_e32 v181, 31, v180
	v_lshlrev_b64 v[226:227], 5, v[180:181]
	v_lshl_add_u64 v[226:227], s[8:9], 0, v[226:227]
	v_cvt_f32_i32_e32 v127, v127
	v_cvt_f32_i32_e32 v126, v126
	v_cvt_f32_i32_e32 v123, v123
	v_cvt_f32_i32_e32 v122, v122
	v_cvt_f32_i32_e32 v119, v119
	v_cvt_f32_i32_e32 v118, v118
	v_cvt_f32_i32_e32 v115, v115
	v_cvt_f32_i32_e32 v114, v114
	v_cvt_f32_i32_e32 v129, v129
	v_cvt_f32_i32_e32 v128, v128
	v_cvt_f32_i32_e32 v117, v117
	v_pk_mul_f32 v[114:115], v[114:115], v[118:119]
	v_cvt_f32_i32_e32 v116, v116
	s_movk_i32 s23, 0x2c00
	v_cvt_f32_i32_e32 v111, v111
	v_cvt_f32_i32_e32 v110, v110
	v_cvt_f32_i32_e32 v107, v107
	v_cvt_f32_i32_e32 v106, v106
	v_cvt_f32_i32_e32 v103, v103
	v_cvt_f32_i32_e32 v102, v102
	v_cvt_f32_i32_e32 v99, v99
	v_pk_mul_f32 v[106:107], v[106:107], v[110:111]
	v_cvt_f32_i32_e32 v98, v98
	v_cvt_f32_i32_e32 v109, v109
	v_cvt_f32_i32_e32 v108, v108
	v_cvt_f32_i32_e32 v101, v101
	v_pk_mul_f32 v[98:99], v[98:99], v[102:103]
	v_cvt_f32_i32_e32 v100, v100
	v_cvt_f32_i32_e32 v95, v95
	v_cvt_f32_i32_e32 v94, v94
	v_cvt_f32_i32_e32 v91, v91
	v_cvt_f32_i32_e32 v90, v90
	v_cvt_f32_i32_e32 v87, v87
	v_cvt_f32_i32_e32 v86, v86
	v_cvt_f32_i32_e32 v83, v83
	v_pk_mul_f32 v[90:91], v[90:91], v[94:95]
	v_cvt_f32_i32_e32 v82, v82
	v_cvt_f32_i32_e32 v93, v93
	v_cvt_f32_i32_e32 v92, v92
	v_cvt_f32_i32_e32 v85, v85
	v_pk_mul_f32 v[82:83], v[82:83], v[86:87]
	v_cvt_f32_i32_e32 v84, v84
	v_cvt_f32_i32_e32 v79, v79
	v_cvt_f32_i32_e32 v78, v78
	v_cvt_f32_i32_e32 v75, v75
	v_cvt_f32_i32_e32 v74, v74
	v_cvt_f32_i32_e32 v71, v71
	v_cvt_f32_i32_e32 v70, v70
	v_cvt_f32_i32_e32 v67, v67
	v_pk_mul_f32 v[74:75], v[74:75], v[78:79]
	v_cvt_f32_i32_e32 v66, v66
	v_cvt_f32_i32_e32 v77, v77
	v_cvt_f32_i32_e32 v76, v76
	v_cvt_f32_i32_e32 v69, v69
	v_pk_mul_f32 v[66:67], v[66:67], v[70:71]
	v_cvt_f32_i32_e32 v68, v68
	v_cvt_f32_i32_e32 v63, v63
	v_cvt_f32_i32_e32 v62, v62
	v_cvt_f32_i32_e32 v59, v59
	v_cvt_f32_i32_e32 v58, v58
	v_cvt_f32_i32_e32 v55, v55
	v_cvt_f32_i32_e32 v54, v54
	v_cvt_f32_i32_e32 v51, v51
	v_pk_mul_f32 v[58:59], v[58:59], v[62:63]
	v_cvt_f32_i32_e32 v50, v50
	v_cvt_f32_i32_e32 v61, v61
	v_cvt_f32_i32_e32 v60, v60
	v_pk_mul_f32 v[50:51], v[50:51], v[54:55]
	v_lshlrev_b64 v[130:131], 5, v[198:199]
	v_lshl_add_u64 v[130:131], s[8:9], 0, v[130:131]
	global_load_dwordx4 v[222:225], v[130:131], off
	global_load_dwordx4 v[236:239], v[130:131], off offset:16
	v_lshlrev_b64 v[130:131], 5, v[192:193]
	v_lshl_add_u64 v[130:131], s[8:9], 0, v[130:131]
	global_load_dwordx4 v[150:153], v[130:131], off
	global_load_dwordx4 v[146:149], v[130:131], off offset:16
	v_lshlrev_b64 v[130:131], 5, v[190:191]
	v_lshl_add_u64 v[130:131], s[8:9], 0, v[130:131]
	global_load_dwordx4 v[134:137], v[130:131], off
	s_nop 0
	global_load_dwordx4 v[130:133], v[130:131], off offset:16
	s_nop 0
	global_load_dwordx4 v[142:145], v[138:139], off
	s_nop 0
	global_load_dwordx4 v[138:141], v[138:139], off offset:16
	s_nop 0
	global_load_dwordx4 v[174:177], v[154:155], off
	global_load_dwordx4 v[166:169], v[154:155], off offset:16
	v_lshlrev_b64 v[154:155], 5, v[184:185]
	v_lshl_add_u64 v[154:155], s[8:9], 0, v[154:155]
	global_load_dwordx4 v[170:173], v[154:155], off
	global_load_dwordx4 v[162:165], v[154:155], off offset:16
	v_lshlrev_b64 v[154:155], 5, v[182:183]
	v_lshl_add_u64 v[154:155], s[8:9], 0, v[154:155]
	global_load_dwordx4 v[158:161], v[154:155], off
	s_nop 0
	global_load_dwordx4 v[154:157], v[154:155], off offset:16
	s_nop 0
	global_load_dwordx4 v[240:243], v[226:227], off
	global_load_dwordx4 v[244:247], v[226:227], off offset:16
	v_cvt_f32_i32_e32 v53, v53
	v_cvt_f32_i32_e32 v52, v52
	v_cvt_f32_i32_e32 v47, v47
	v_cvt_f32_i32_e32 v46, v46
	v_cvt_f32_i32_e32 v43, v43
	v_cvt_f32_i32_e32 v42, v42
	v_cvt_f32_i32_e32 v39, v39
	v_cvt_f32_i32_e32 v38, v38
	v_cvt_f32_i32_e32 v35, v35
	v_pk_mul_f32 v[42:43], v[42:43], v[46:47]
	v_cvt_f32_i32_e32 v34, v34
	v_cvt_f32_i32_e32 v45, v45
	v_cvt_f32_i32_e32 v44, v44
	v_cvt_f32_i32_e32 v37, v37
	v_pk_mul_f32 v[34:35], v[34:35], v[38:39]
	v_cvt_f32_i32_e32 v36, v36
	v_cvt_f32_i32_e32 v31, v31
	v_cvt_f32_i32_e32 v30, v30
	v_cvt_f32_i32_e32 v27, v27
	v_cvt_f32_i32_e32 v26, v26
	v_cvt_f32_i32_e32 v23, v23
	v_cvt_f32_i32_e32 v22, v22
	v_cvt_f32_i32_e32 v19, v19
	v_pk_mul_f32 v[26:27], v[26:27], v[30:31]
	v_cvt_f32_i32_e32 v18, v18
	v_cvt_f32_i32_e32 v29, v29
	v_cvt_f32_i32_e32 v28, v28
	v_cvt_f32_i32_e32 v21, v21
	v_pk_mul_f32 v[18:19], v[18:19], v[22:23]
	v_cvt_f32_i32_e32 v20, v20
	v_cvt_f32_i32_e32 v15, v15
	v_cvt_f32_i32_e32 v14, v14
	v_cvt_f32_i32_e32 v11, v11
	v_cvt_f32_i32_e32 v10, v10
	v_cvt_f32_i32_e32 v7, v7
	v_cvt_f32_i32_e32 v6, v6
	v_cvt_f32_i32_e32 v3, v3
	v_pk_mul_f32 v[10:11], v[10:11], v[14:15]
	v_cvt_f32_i32_e32 v2, v2
	v_cvt_f32_i32_e32 v13, v13
	v_cvt_f32_i32_e32 v12, v12
	v_cvt_f32_i32_e32 v5, v5
	v_pk_mul_f32 v[2:3], v[2:3], v[6:7]
	v_cvt_f32_i32_e32 v4, v4
	s_mov_b64 s[42:43], -1
	s_andn2_b64 vcc, exec, s[38:39]
	s_waitcnt vmcnt(15)
	v_pk_mul_f32 v[196:197], v[250:251], s[28:29] op_sel_hi:[1,0]
	v_pk_mul_f32 v[200:201], v[252:253], s[28:29] op_sel_hi:[1,0]
	v_mul_f32_e32 v254, v196, v197
	v_rcp_f32_e32 v212, v254
	v_mul_f32_e32 v255, v200, v201
	v_rcp_f32_e32 v213, v255
	v_mov_b32_e32 v197, v219
	v_mov_b32_e32 v201, v220
	v_mov_b32_e32 v226, v222
	s_waitcnt vmcnt(14)
	v_mov_b32_e32 v227, v236
	v_mov_b32_e32 v236, v223
	v_pk_add_f32 v[222:223], v[226:227], v[236:237]
	v_mov_b32_e32 v226, v224
	v_mov_b32_e32 v227, v238
	v_mov_b32_e32 v238, v225
	v_pk_add_f32 v[224:225], v[226:227], v[238:239]
	s_nop 0
	v_pk_add_f32 v[222:223], v[222:223], v[224:225]
	s_nop 0
	v_add_f32_e32 v181, v222, v223
	s_waitcnt vmcnt(13)
	v_mov_b32_e32 v222, v150
	s_waitcnt vmcnt(12)
	v_mov_b32_e32 v223, v146
	v_mov_b32_e32 v146, v151
	v_mov_b32_e32 v150, v152
	v_mov_b32_e32 v151, v148
	v_mov_b32_e32 v148, v153
	v_pk_add_f32 v[146:147], v[222:223], v[146:147]
	v_pk_add_f32 v[148:149], v[150:151], v[148:149]
	v_fmamk_f32 v181, v181, 0x3a000000, v1
	v_pk_add_f32 v[146:147], v[146:147], v[148:149]
	v_rsq_f32_e32 v207, v181
	v_add_f32_e32 v146, v146, v147
	v_fmamk_f32 v146, v146, 0x3a000000, v1
	v_rsq_f32_e32 v148, v146
	s_waitcnt vmcnt(11)
	v_mov_b32_e32 v146, v134
	s_waitcnt vmcnt(10)
	v_mov_b32_e32 v147, v130
	v_mov_b32_e32 v130, v135
	v_mov_b32_e32 v134, v136
	v_mov_b32_e32 v135, v132
	v_mov_b32_e32 v132, v137
	v_pk_add_f32 v[130:131], v[146:147], v[130:131]
	v_pk_add_f32 v[132:133], v[134:135], v[132:133]
	s_nop 0
	v_pk_add_f32 v[130:131], v[130:131], v[132:133]
	s_waitcnt vmcnt(9)
	v_mov_b32_e32 v132, v144
	v_add_f32_e32 v130, v130, v131
	v_fmamk_f32 v130, v130, 0x3a000000, v1
	v_rsq_f32_e32 v146, v130
	v_mov_b32_e32 v130, v142
	s_waitcnt vmcnt(8)
	v_mov_b32_e32 v131, v138
	v_mov_b32_e32 v138, v143
	v_mov_b32_e32 v133, v140
	v_mov_b32_e32 v140, v145
	v_pk_add_f32 v[130:131], v[130:131], v[138:139]
	v_pk_add_f32 v[132:133], v[132:133], v[140:141]
	v_pk_mul_f32 v[142:143], v[122:123], v[126:127]
	v_pk_add_f32 v[130:131], v[130:131], v[132:133]
	s_waitcnt vmcnt(7)
	v_mov_b32_e32 v132, v176
	v_add_f32_e32 v130, v130, v131
	v_fmamk_f32 v130, v130, 0x3a000000, v1
	v_rsq_f32_e32 v138, v130
	v_mov_b32_e32 v130, v174
	s_waitcnt vmcnt(6)
	v_mov_b32_e32 v131, v166
	v_mov_b32_e32 v166, v175
	v_mov_b32_e32 v133, v168
	v_mov_b32_e32 v168, v177
	v_pk_add_f32 v[130:131], v[130:131], v[166:167]
	v_pk_add_f32 v[132:133], v[132:133], v[168:169]
	s_nop 0
	v_pk_add_f32 v[130:131], v[130:131], v[132:133]
	s_waitcnt vmcnt(5)
	v_mov_b32_e32 v132, v172
	v_add_f32_e32 v130, v130, v131
	v_fmamk_f32 v130, v130, 0x3a000000, v1
	v_rsq_f32_e32 v137, v130
	v_mov_b32_e32 v130, v170
	s_waitcnt vmcnt(4)
	v_mov_b32_e32 v131, v162
	v_mov_b32_e32 v162, v171
	v_mov_b32_e32 v133, v164
	v_mov_b32_e32 v164, v173
	v_pk_add_f32 v[130:131], v[130:131], v[162:163]
	v_pk_add_f32 v[132:133], v[132:133], v[164:165]
	s_nop 0
	v_pk_add_f32 v[130:131], v[130:131], v[132:133]
	s_waitcnt vmcnt(3)
	v_mov_b32_e32 v132, v160
	v_add_f32_e32 v130, v130, v131
	v_fmamk_f32 v130, v130, 0x3a000000, v1
	v_rsq_f32_e32 v136, v130
	v_mov_b32_e32 v130, v158
	s_waitcnt vmcnt(2)
	v_mov_b32_e32 v131, v154
	v_mov_b32_e32 v154, v159
	v_mov_b32_e32 v133, v156
	v_mov_b32_e32 v156, v161
	v_pk_add_f32 v[130:131], v[130:131], v[154:155]
	v_pk_add_f32 v[132:133], v[132:133], v[156:157]
	s_nop 0
	v_pk_add_f32 v[130:131], v[130:131], v[132:133]
	s_waitcnt vmcnt(1)
	v_mov_b32_e32 v132, v242
	v_add_f32_e32 v130, v130, v131
	v_fmamk_f32 v130, v130, 0x3a000000, v1
	v_rsq_f32_e32 v135, v130
	v_mov_b32_e32 v130, v240
	s_waitcnt vmcnt(0)
	v_mov_b32_e32 v131, v244
	v_mov_b32_e32 v244, v241
	v_mov_b32_e32 v133, v246
	v_mov_b32_e32 v246, v243
	v_pk_add_f32 v[130:131], v[130:131], v[244:245]
	v_pk_add_f32 v[132:133], v[132:133], v[246:247]
	s_nop 0
	v_pk_add_f32 v[130:131], v[130:131], v[132:133]
	v_pk_mul_f32 v[132:133], v[200:201], v[206:207]
	v_mov_b32_e32 v207, v148
	v_mul_f32_e32 v139, v133, v133
	v_mul_f32_e32 v145, v132, v133
	v_rcp_f32_e32 v139, v139
	v_mul_f32_e32 v122, v145, v118
	v_mul_f32_e32 v123, v145, v119
	v_exp_f32_e32 v122, v122
	v_exp_f32_e32 v123, v123
	v_mul_f32_e32 v144, v212, v139
	v_mul_f32_e32 v139, v213, v139
	v_fma_f32 v122, v122, v139, v139
	v_fma_f32 v118, v123, v139, v139
	v_rcp_f32_e32 v122, v122
	v_rcp_f32_e32 v123, v118
	v_add_f32_e32 v130, v130, v131
	v_fmamk_f32 v130, v130, 0x3a000000, v1
	v_rsq_f32_e32 v134, v130
	v_pk_mul_f32 v[118:119], v[114:115], v[122:123]
	v_cvt_f32_i32_e32 v115, v125
	v_cvt_f32_i32_e32 v114, v124
	v_mov_b64_e32 v[130:131], s[6:7]
	v_mad_i64_i32 v[140:141], s[28:29], v198, s23, v[130:131]
	v_pk_mul_f32 v[124:125], v[114:115], v[128:129]
	v_cvt_f32_i32_e32 v115, v121
	v_cvt_f32_i32_e32 v114, v120
	v_cvt_pk_bf16_f32 v122, v118, v119
	v_mad_i64_i32 v[118:119], s[28:29], v192, s23, v[130:131]
	v_mul_f32_e32 v120, v145, v114
	v_mul_f32_e32 v121, v145, v115
	v_exp_f32_e32 v120, v120
	v_exp_f32_e32 v121, v121
	v_pk_mul_f32 v[114:115], v[116:117], v[114:115]
	v_fma_f32 v120, v120, v139, v139
	v_fmac_f32_e32 v139, v121, v139
	v_rcp_f32_e32 v120, v120
	v_rcp_f32_e32 v121, v139
	s_nop 0
	v_pk_mul_f32 v[116:117], v[114:115], v[120:121]
	s_nop 0
	v_cvt_pk_bf16_f32 v123, v116, v117
	v_pk_mul_f32 v[116:117], v[196:197], v[206:207]
	v_lshlrev_b64 v[114:115], 1, v[194:195]
	v_mul_f32_e32 v133, v116, v133
	v_mul_f32_e32 v120, v133, v126
	v_mul_f32_e32 v121, v133, v127
	v_mul_f32_e32 v126, v133, v128
	v_mul_f32_e32 v127, v133, v129
	v_exp_f32_e32 v120, v120
	v_exp_f32_e32 v121, v121
	v_exp_f32_e32 v126, v126
	v_exp_f32_e32 v127, v127
	v_fma_f32 v120, v120, v144, v144
	v_fma_f32 v121, v121, v144, v144
	v_fma_f32 v126, v126, v144, v144
	v_fmac_f32_e32 v144, v127, v144
	v_rcp_f32_e32 v120, v120
	v_rcp_f32_e32 v121, v121
	v_rcp_f32_e32 v126, v126
	v_rcp_f32_e32 v127, v144
	v_lshl_add_u64 v[140:141], v[140:141], 0, v[114:115]
	v_pk_mul_f32 v[120:121], v[142:143], v[120:121]
	v_pk_mul_f32 v[124:125], v[124:125], v[126:127]
	v_cvt_pk_bf16_f32 v120, v120, v121
	v_cvt_pk_bf16_f32 v121, v124, v125
	global_store_dwordx4 v[140:141], v[120:123], off
	v_mul_f32_e32 v124, v116, v117
	s_nop 0
	v_mul_f32_e32 v120, v117, v117
	v_rcp_f32_e32 v120, v120
	v_mul_f32_e32 v121, v124, v111
	v_exp_f32_e32 v121, v121
	v_mul_f32_e32 v117, v132, v117
	v_mul_f32_e32 v122, v212, v120
	v_mul_f32_e32 v123, v213, v120
	v_mul_f32_e32 v120, v124, v110
	v_fma_f32 v110, v121, v122, v122
	v_rcp_f32_e32 v121, v110
	v_mul_f32_e32 v110, v117, v102
	v_mul_f32_e32 v111, v117, v103
	v_exp_f32_e32 v110, v110
	v_exp_f32_e32 v111, v111
	v_exp_f32_e32 v120, v120
	v_fma_f32 v110, v110, v123, v123
	v_fma_f32 v102, v111, v123, v123
	v_rcp_f32_e32 v110, v110
	v_rcp_f32_e32 v111, v102
	v_fma_f32 v120, v120, v122, v122
	v_rcp_f32_e32 v120, v120
	v_pk_mul_f32 v[102:103], v[98:99], v[110:111]
	v_cvt_f32_i32_e32 v99, v113
	v_cvt_f32_i32_e32 v98, v112
	v_pk_mul_f32 v[106:107], v[106:107], v[120:121]
	v_mul_f32_e32 v111, v124, v99
	v_mul_f32_e32 v110, v124, v98
	v_exp_f32_e32 v110, v110
	v_exp_f32_e32 v111, v111
	v_pk_mul_f32 v[98:99], v[108:109], v[98:99]
	v_fma_f32 v110, v110, v122, v122
	v_fmac_f32_e32 v122, v111, v122
	v_rcp_f32_e32 v110, v110
	v_rcp_f32_e32 v111, v122
	s_nop 0
	v_pk_mul_f32 v[108:109], v[98:99], v[110:111]
	v_cvt_f32_i32_e32 v99, v105
	v_cvt_f32_i32_e32 v98, v104
	v_lshl_add_u64 v[110:111], v[118:119], 0, v[114:115]
	v_mul_f32_e32 v105, v117, v99
	v_mul_f32_e32 v104, v117, v98
	v_exp_f32_e32 v104, v104
	v_exp_f32_e32 v105, v105
	v_pk_mul_f32 v[98:99], v[100:101], v[98:99]
	v_cvt_pk_bf16_f32 v100, v102, v103
	v_fma_f32 v104, v104, v123, v123
	v_fmac_f32_e32 v123, v105, v123
	v_rcp_f32_e32 v104, v104
	v_rcp_f32_e32 v105, v123
	s_nop 0
	v_pk_mul_f32 v[104:105], v[98:99], v[104:105]
	v_cvt_pk_bf16_f32 v98, v106, v107
	v_cvt_pk_bf16_f32 v99, v108, v109
	v_cvt_pk_bf16_f32 v101, v104, v105
	global_store_dwordx4 v[110:111], v[98:101], off
	s_nop 1
	v_mul_f32_e32 v100, v218, v146
	v_mul_f32_e32 v101, v100, v100
	v_rcp_f32_e32 v101, v101
	v_mul_f32_e32 v102, v116, v100
	v_mul_f32_e32 v103, v132, v100
	v_mul_f32_e32 v100, v102, v94
	v_mul_f32_e32 v104, v212, v101
	v_mul_f32_e32 v105, v213, v101
	v_mul_f32_e32 v101, v102, v95
	v_exp_f32_e32 v101, v101
	v_mul_f32_e32 v95, v103, v87
	v_exp_f32_e32 v95, v95
	v_exp_f32_e32 v100, v100
	v_fma_f32 v94, v101, v104, v104
	v_rcp_f32_e32 v101, v94
	v_mul_f32_e32 v94, v103, v86
	v_exp_f32_e32 v94, v94
	v_fma_f32 v86, v95, v105, v105
	v_rcp_f32_e32 v95, v86
	v_fma_f32 v100, v100, v104, v104
	v_fma_f32 v94, v94, v105, v105
	v_rcp_f32_e32 v94, v94
	v_rcp_f32_e32 v100, v100
	v_mad_i64_i32 v[98:99], s[28:29], v190, s23, v[130:131]
	v_pk_mul_f32 v[86:87], v[82:83], v[94:95]
	v_cvt_f32_i32_e32 v83, v97
	v_cvt_f32_i32_e32 v82, v96
	v_pk_mul_f32 v[90:91], v[90:91], v[100:101]
	v_mul_f32_e32 v95, v102, v83
	v_mul_f32_e32 v94, v102, v82
	v_exp_f32_e32 v94, v94
	v_exp_f32_e32 v95, v95
	v_pk_mul_f32 v[82:83], v[92:93], v[82:83]
	v_fma_f32 v94, v94, v104, v104
	v_fmac_f32_e32 v104, v95, v104
	v_rcp_f32_e32 v94, v94
	v_rcp_f32_e32 v95, v104
	s_nop 0
	v_pk_mul_f32 v[92:93], v[82:83], v[94:95]
	v_cvt_f32_i32_e32 v83, v89
	v_cvt_f32_i32_e32 v82, v88
	v_lshl_add_u64 v[94:95], v[98:99], 0, v[114:115]
	v_mul_f32_e32 v89, v103, v83
	v_mul_f32_e32 v88, v103, v82
	v_exp_f32_e32 v88, v88
	v_exp_f32_e32 v89, v89
	v_pk_mul_f32 v[82:83], v[84:85], v[82:83]
	v_cvt_pk_bf16_f32 v84, v86, v87
	v_fma_f32 v88, v88, v105, v105
	v_fmac_f32_e32 v105, v89, v105
	v_rcp_f32_e32 v88, v88
	v_rcp_f32_e32 v89, v105
	s_nop 0
	v_pk_mul_f32 v[88:89], v[82:83], v[88:89]
	v_cvt_pk_bf16_f32 v82, v90, v91
	v_cvt_pk_bf16_f32 v83, v92, v93
	v_cvt_pk_bf16_f32 v85, v88, v89
	global_store_dwordx4 v[94:95], v[82:85], off
	s_nop 1
	v_mul_f32_e32 v84, v217, v138
	v_mul_f32_e32 v85, v84, v84
	v_rcp_f32_e32 v85, v85
	v_mul_f32_e32 v86, v116, v84
	v_mul_f32_e32 v87, v132, v84
	v_mul_f32_e32 v84, v86, v78
	v_mul_f32_e32 v88, v212, v85
	v_mul_f32_e32 v89, v213, v85
	v_mul_f32_e32 v85, v86, v79
	v_exp_f32_e32 v85, v85
	v_mul_f32_e32 v79, v87, v71
	v_exp_f32_e32 v79, v79
	v_exp_f32_e32 v84, v84
	v_fma_f32 v78, v85, v88, v88
	v_rcp_f32_e32 v85, v78
	v_mul_f32_e32 v78, v87, v70
	v_exp_f32_e32 v78, v78
	v_fma_f32 v70, v79, v89, v89
	v_rcp_f32_e32 v79, v70
	v_fma_f32 v84, v84, v88, v88
	v_fma_f32 v78, v78, v89, v89
	v_rcp_f32_e32 v78, v78
	v_rcp_f32_e32 v84, v84
	v_mad_i64_i32 v[82:83], s[28:29], v188, s23, v[130:131]
	v_pk_mul_f32 v[70:71], v[66:67], v[78:79]
	v_cvt_f32_i32_e32 v67, v81
	v_cvt_f32_i32_e32 v66, v80
	v_pk_mul_f32 v[74:75], v[74:75], v[84:85]
	v_mul_f32_e32 v79, v86, v67
	v_mul_f32_e32 v78, v86, v66
	v_exp_f32_e32 v78, v78
	v_exp_f32_e32 v79, v79
	v_pk_mul_f32 v[66:67], v[76:77], v[66:67]
	v_fma_f32 v78, v78, v88, v88
	v_fmac_f32_e32 v88, v79, v88
	v_rcp_f32_e32 v78, v78
	v_rcp_f32_e32 v79, v88
	s_nop 0
	v_pk_mul_f32 v[76:77], v[66:67], v[78:79]
	v_cvt_f32_i32_e32 v67, v73
	v_cvt_f32_i32_e32 v66, v72
	v_lshl_add_u64 v[78:79], v[82:83], 0, v[114:115]
	v_mul_f32_e32 v73, v87, v67
	v_mul_f32_e32 v72, v87, v66
	v_exp_f32_e32 v72, v72
	v_exp_f32_e32 v73, v73
	v_pk_mul_f32 v[66:67], v[68:69], v[66:67]
	v_cvt_pk_bf16_f32 v68, v70, v71
	v_fma_f32 v72, v72, v89, v89
	v_fmac_f32_e32 v89, v73, v89
	v_rcp_f32_e32 v72, v72
	v_rcp_f32_e32 v73, v89
	s_nop 0
	v_pk_mul_f32 v[72:73], v[66:67], v[72:73]
	v_cvt_pk_bf16_f32 v66, v74, v75
	v_cvt_pk_bf16_f32 v67, v76, v77
	v_cvt_pk_bf16_f32 v69, v72, v73
	global_store_dwordx4 v[78:79], v[66:69], off
	s_nop 1
	v_mul_f32_e32 v68, v216, v137
	v_mul_f32_e32 v69, v68, v68
	v_rcp_f32_e32 v69, v69
	v_mul_f32_e32 v70, v116, v68
	v_mul_f32_e32 v71, v132, v68
	v_mul_f32_e32 v68, v70, v62
	v_mul_f32_e32 v72, v212, v69
	v_mul_f32_e32 v73, v213, v69
	v_mul_f32_e32 v69, v70, v63
	v_exp_f32_e32 v69, v69
	v_mul_f32_e32 v63, v71, v55
	v_exp_f32_e32 v63, v63
	v_exp_f32_e32 v68, v68
	v_fma_f32 v62, v69, v72, v72
	v_rcp_f32_e32 v69, v62
	v_mul_f32_e32 v62, v71, v54
	v_exp_f32_e32 v62, v62
	v_fma_f32 v54, v63, v73, v73
	v_rcp_f32_e32 v63, v54
	v_fma_f32 v68, v68, v72, v72
	v_fma_f32 v62, v62, v73, v73
	v_rcp_f32_e32 v62, v62
	v_rcp_f32_e32 v68, v68
	v_mad_i64_i32 v[66:67], s[28:29], v186, s23, v[130:131]
	v_pk_mul_f32 v[54:55], v[50:51], v[62:63]
	v_cvt_f32_i32_e32 v51, v65
	v_cvt_f32_i32_e32 v50, v64
	v_pk_mul_f32 v[58:59], v[58:59], v[68:69]
	v_mul_f32_e32 v63, v70, v51
	v_mul_f32_e32 v62, v70, v50
	v_exp_f32_e32 v62, v62
	v_exp_f32_e32 v63, v63
	v_pk_mul_f32 v[50:51], v[60:61], v[50:51]
	v_fma_f32 v62, v62, v72, v72
	v_fmac_f32_e32 v72, v63, v72
	v_rcp_f32_e32 v62, v62
	v_rcp_f32_e32 v63, v72
	s_nop 0
	v_pk_mul_f32 v[60:61], v[50:51], v[62:63]
	v_cvt_f32_i32_e32 v51, v57
	v_cvt_f32_i32_e32 v50, v56
	v_lshl_add_u64 v[62:63], v[66:67], 0, v[114:115]
	v_mul_f32_e32 v57, v71, v51
	v_mul_f32_e32 v56, v71, v50
	v_exp_f32_e32 v56, v56
	v_exp_f32_e32 v57, v57
	v_pk_mul_f32 v[50:51], v[52:53], v[50:51]
	v_cvt_pk_bf16_f32 v52, v54, v55
	v_fma_f32 v56, v56, v73, v73
	v_fmac_f32_e32 v73, v57, v73
	v_rcp_f32_e32 v56, v56
	v_rcp_f32_e32 v57, v73
	s_nop 0
	v_pk_mul_f32 v[56:57], v[50:51], v[56:57]
	v_cvt_pk_bf16_f32 v50, v58, v59
	v_cvt_pk_bf16_f32 v51, v60, v61
	v_cvt_pk_bf16_f32 v53, v56, v57
	global_store_dwordx4 v[62:63], v[50:53], off
	s_nop 1
	v_mul_f32_e32 v52, v215, v136
	v_mul_f32_e32 v53, v52, v52
	v_rcp_f32_e32 v53, v53
	v_mul_f32_e32 v54, v116, v52
	v_mul_f32_e32 v55, v132, v52
	v_mul_f32_e32 v52, v54, v46
	v_mul_f32_e32 v56, v212, v53
	v_mul_f32_e32 v57, v213, v53
	v_mul_f32_e32 v53, v54, v47
	v_exp_f32_e32 v53, v53
	v_mul_f32_e32 v47, v55, v39
	v_exp_f32_e32 v47, v47
	v_exp_f32_e32 v52, v52
	v_fma_f32 v46, v53, v56, v56
	v_rcp_f32_e32 v53, v46
	v_mul_f32_e32 v46, v55, v38
	v_exp_f32_e32 v46, v46
	v_fma_f32 v38, v47, v57, v57
	v_rcp_f32_e32 v47, v38
	v_fma_f32 v52, v52, v56, v56
	v_fma_f32 v46, v46, v57, v57
	v_rcp_f32_e32 v46, v46
	v_rcp_f32_e32 v52, v52
	v_mad_i64_i32 v[50:51], s[28:29], v184, s23, v[130:131]
	v_pk_mul_f32 v[38:39], v[34:35], v[46:47]
	v_cvt_f32_i32_e32 v35, v49
	v_cvt_f32_i32_e32 v34, v48
	v_pk_mul_f32 v[42:43], v[42:43], v[52:53]
	v_mul_f32_e32 v47, v54, v35
	v_mul_f32_e32 v46, v54, v34
	v_exp_f32_e32 v46, v46
	v_exp_f32_e32 v47, v47
	v_pk_mul_f32 v[34:35], v[44:45], v[34:35]
	v_fma_f32 v46, v46, v56, v56
	v_fmac_f32_e32 v56, v47, v56
	v_rcp_f32_e32 v46, v46
	v_rcp_f32_e32 v47, v56
	s_nop 0
	v_pk_mul_f32 v[44:45], v[34:35], v[46:47]
	v_cvt_f32_i32_e32 v35, v41
	v_cvt_f32_i32_e32 v34, v40
	v_lshl_add_u64 v[46:47], v[50:51], 0, v[114:115]
	v_mul_f32_e32 v41, v55, v35
	v_mul_f32_e32 v40, v55, v34
	v_exp_f32_e32 v40, v40
	v_exp_f32_e32 v41, v41
	v_pk_mul_f32 v[34:35], v[36:37], v[34:35]
	v_cvt_pk_bf16_f32 v36, v38, v39
	v_fma_f32 v40, v40, v57, v57
	v_fmac_f32_e32 v57, v41, v57
	v_rcp_f32_e32 v40, v40
	v_rcp_f32_e32 v41, v57
	s_nop 0
	v_pk_mul_f32 v[40:41], v[34:35], v[40:41]
	v_cvt_pk_bf16_f32 v34, v42, v43
	v_cvt_pk_bf16_f32 v35, v44, v45
	v_cvt_pk_bf16_f32 v37, v40, v41
	global_store_dwordx4 v[46:47], v[34:37], off
	s_nop 1
	v_mul_f32_e32 v36, v214, v135
	v_mul_f32_e32 v37, v36, v36
	v_rcp_f32_e32 v37, v37
	v_mul_f32_e32 v38, v116, v36
	v_mul_f32_e32 v39, v132, v36
	v_mul_f32_e32 v36, v38, v30
	v_mul_f32_e32 v40, v212, v37
	v_mul_f32_e32 v41, v213, v37
	v_mul_f32_e32 v37, v38, v31
	v_exp_f32_e32 v37, v37
	v_mul_f32_e32 v31, v39, v23
	v_exp_f32_e32 v31, v31
	v_exp_f32_e32 v36, v36
	v_fma_f32 v30, v37, v40, v40
	v_rcp_f32_e32 v37, v30
	v_mul_f32_e32 v30, v39, v22
	v_exp_f32_e32 v30, v30
	v_fma_f32 v22, v31, v41, v41
	v_rcp_f32_e32 v31, v22
	v_fma_f32 v36, v36, v40, v40
	v_fma_f32 v30, v30, v41, v41
	v_rcp_f32_e32 v30, v30
	v_rcp_f32_e32 v36, v36
	v_mad_i64_i32 v[34:35], s[28:29], v182, s23, v[130:131]
	v_pk_mul_f32 v[22:23], v[18:19], v[30:31]
	v_cvt_f32_i32_e32 v19, v33
	v_cvt_f32_i32_e32 v18, v32
	v_pk_mul_f32 v[26:27], v[26:27], v[36:37]
	v_mul_f32_e32 v31, v38, v19
	v_mul_f32_e32 v30, v38, v18
	v_exp_f32_e32 v30, v30
	v_exp_f32_e32 v31, v31
	v_pk_mul_f32 v[18:19], v[28:29], v[18:19]
	v_fma_f32 v30, v30, v40, v40
	v_fmac_f32_e32 v40, v31, v40
	v_rcp_f32_e32 v30, v30
	v_rcp_f32_e32 v31, v40
	s_nop 0
	v_pk_mul_f32 v[28:29], v[18:19], v[30:31]
	v_cvt_f32_i32_e32 v19, v25
	v_cvt_f32_i32_e32 v18, v24
	v_lshl_add_u64 v[30:31], v[34:35], 0, v[114:115]
	v_mul_f32_e32 v25, v39, v19
	v_mul_f32_e32 v24, v39, v18
	v_exp_f32_e32 v24, v24
	v_exp_f32_e32 v25, v25
	v_pk_mul_f32 v[18:19], v[20:21], v[18:19]
	v_cvt_pk_bf16_f32 v20, v22, v23
	v_fma_f32 v24, v24, v41, v41
	v_fmac_f32_e32 v41, v25, v41
	v_rcp_f32_e32 v24, v24
	v_rcp_f32_e32 v25, v41
	s_nop 0
	v_pk_mul_f32 v[24:25], v[18:19], v[24:25]
	v_cvt_pk_bf16_f32 v18, v26, v27
	v_cvt_pk_bf16_f32 v19, v28, v29
	v_cvt_pk_bf16_f32 v21, v24, v25
	global_store_dwordx4 v[30:31], v[18:21], off
	s_nop 1
	v_mul_f32_e32 v20, v211, v134
	v_mul_f32_e32 v21, v20, v20
	v_rcp_f32_e32 v21, v21
	v_mul_f32_e32 v22, v116, v20
	v_mul_f32_e32 v23, v132, v20
	v_mul_f32_e32 v20, v22, v14
	v_mul_f32_e32 v24, v212, v21
	v_mul_f32_e32 v25, v213, v21
	v_mul_f32_e32 v21, v22, v15
	v_exp_f32_e32 v21, v21
	v_mul_f32_e32 v15, v23, v7
	v_exp_f32_e32 v15, v15
	v_exp_f32_e32 v20, v20
	v_fma_f32 v14, v21, v24, v24
	v_rcp_f32_e32 v21, v14
	v_mul_f32_e32 v14, v23, v6
	v_exp_f32_e32 v14, v14
	v_fma_f32 v6, v15, v25, v25
	v_rcp_f32_e32 v15, v6
	v_fma_f32 v20, v20, v24, v24
	v_fma_f32 v14, v14, v25, v25
	v_rcp_f32_e32 v14, v14
	v_rcp_f32_e32 v20, v20
	v_mad_i64_i32 v[18:19], s[28:29], v180, s23, v[130:131]
	v_pk_mul_f32 v[6:7], v[2:3], v[14:15]
	v_cvt_f32_i32_e32 v3, v17
	v_cvt_f32_i32_e32 v2, v16
	v_pk_mul_f32 v[10:11], v[10:11], v[20:21]
	v_mul_f32_e32 v15, v22, v3
	v_mul_f32_e32 v14, v22, v2
	v_exp_f32_e32 v14, v14
	v_exp_f32_e32 v15, v15
	v_pk_mul_f32 v[2:3], v[12:13], v[2:3]
	v_fma_f32 v14, v14, v24, v24
	v_fmac_f32_e32 v24, v15, v24
	v_rcp_f32_e32 v14, v14
	v_rcp_f32_e32 v15, v24
	s_nop 0
	v_pk_mul_f32 v[12:13], v[2:3], v[14:15]
	v_cvt_f32_i32_e32 v3, v9
	v_cvt_f32_i32_e32 v2, v8
	v_lshl_add_u64 v[14:15], v[18:19], 0, v[114:115]
	v_mul_f32_e32 v9, v23, v3
	v_mul_f32_e32 v8, v23, v2
	v_exp_f32_e32 v8, v8
	v_exp_f32_e32 v9, v9
	v_pk_mul_f32 v[2:3], v[4:5], v[2:3]
	v_cvt_pk_bf16_f32 v4, v6, v7
	v_fma_f32 v8, v8, v25, v25
	v_fmac_f32_e32 v25, v9, v25
	v_rcp_f32_e32 v8, v8
	v_rcp_f32_e32 v9, v25
	s_nop 0
	v_pk_mul_f32 v[8:9], v[2:3], v[8:9]
	v_cvt_pk_bf16_f32 v2, v10, v11
	v_cvt_pk_bf16_f32 v3, v12, v13
	v_cvt_pk_bf16_f32 v5, v8, v9
	global_store_dwordx4 v[14:15], v[2:5], off
	s_cbranch_vccnz .LBB0_1210
	s_andn2_b64 vcc, exec, s[4:5]
	s_cbranch_vccnz .LBB0_1209
	s_barrier
	s_branch .LBB0_1209

	.amdhsa_kernel _Z6mk_fwd4Args
		.amdhsa_group_segment_fixed_size 0
		.amdhsa_private_segment_fixed_size 0
		.amdhsa_kernarg_size 472
		.amdhsa_user_sgpr_count 2
		.amdhsa_user_sgpr_dispatch_ptr 0
		.amdhsa_user_sgpr_queue_ptr 0
		.amdhsa_user_sgpr_kernarg_segment_ptr 1
		.amdhsa_user_sgpr_dispatch_id 0
		.amdhsa_user_sgpr_kernarg_preload_length 0
		.amdhsa_user_sgpr_kernarg_preload_offset 0
		.amdhsa_user_sgpr_private_segment_size 0
		.amdhsa_uses_dynamic_stack 0
		.amdhsa_enable_private_segment 0
		.amdhsa_system_sgpr_workgroup_id_x 1
		.amdhsa_system_sgpr_workgroup_id_y 0
		.amdhsa_system_sgpr_workgroup_id_z 0
		.amdhsa_system_sgpr_workgroup_info 0
		.amdhsa_system_vgpr_workitem_id 0
				.amdhsa_next_free_vgpr 256
		.amdhsa_next_free_sgpr 100
				.amdhsa_accum_offset 256
		.amdhsa_reserve_vcc 1
		.amdhsa_float_round_mode_32 0
		.amdhsa_float_round_mode_16_64 0
		.amdhsa_float_denorm_mode_32 3
		.amdhsa_float_denorm_mode_16_64 3
		.amdhsa_dx10_clamp 1
		.amdhsa_ieee_mode 1
		.amdhsa_fp16_overflow 0
		.amdhsa_tg_split 0
		.amdhsa_exception_fp_ieee_invalid_op 0
		.amdhsa_exception_fp_denorm_src 0
		.amdhsa_exception_fp_ieee_div_zero 0
		.amdhsa_exception_fp_ieee_overflow 0
		.amdhsa_exception_fp_ieee_underflow 0
		.amdhsa_exception_fp_ieee_inexact 0
		.amdhsa_exception_int_div_zero 0
	.end_amdhsa_kernel

amdhsa.kernels:
  - .agpr_count:     0
    .args:
      - .offset:         0
        .size:           216
        .value_kind:     by_value
      - .offset:         216
        .size:           4
        .value_kind:     hidden_block_count_x
      - .offset:         220
        .size:           4
        .value_kind:     hidden_block_count_y
      - .offset:         224
        .size:           4
        .value_kind:     hidden_block_count_z
      - .offset:         228
        .size:           2
        .value_kind:     hidden_group_size_x
      - .offset:         230
        .size:           2
        .value_kind:     hidden_group_size_y
      - .offset:         232
        .size:           2
        .value_kind:     hidden_group_size_z
      - .offset:         234
        .size:           2
        .value_kind:     hidden_remainder_x
      - .offset:         236
        .size:           2
        .value_kind:     hidden_remainder_y
      - .offset:         238
        .size:           2
        .value_kind:     hidden_remainder_z
      - .offset:         256
        .size:           8
        .value_kind:     hidden_global_offset_x
      - .offset:         264
        .size:           8
        .value_kind:     hidden_global_offset_y
      - .offset:         272
        .size:           8
        .value_kind:     hidden_global_offset_z
      - .offset:         280
        .size:           2
        .value_kind:     hidden_grid_dims
      - .offset:         336
        .size:           4
        .value_kind:     hidden_dynamic_lds_size
    .group_segment_fixed_size: 0
    .kernarg_segment_align: 8
    .kernarg_segment_size: 472
    .language:       OpenCL C
    .language_version:
      - 2
      - 0
    .max_flat_workgroup_size: 512
    .name:           _Z6mk_fwd4Args
    .private_segment_fixed_size: 0
    .sgpr_count:     106
    .sgpr_spill_count: 124
    .symbol:         _Z6mk_fwd4Args.kd
    .uniform_work_group_size: 1
    .uses_dynamic_stack: false
    .vgpr_count:     256
    .vgpr_spill_count: 0
    .wavefront_size: 64
